# v119 + phase 0 lane mapping: each lane converts 8 consecutive floats per half row, two 16-byte stores per row instead of four 8-byte stores
# speedup vs baseline: 1.0114x; 1.0001x over previous
.LBB0_18:
	s_or_b64 exec, exec, s[6:7]
	s_mov_b64 s[4:5], src_shared_base
	s_cmp_lg_u32 0, -1
	s_cselect_b32 s3, s5, 0
	s_cselect_b32 s4, 0, 0
	v_mov_b32_e32 v0, s4
	v_mov_b32_e32 v1, s3
	s_waitcnt lgkmcnt(0)
	s_barrier
	flat_load_dword v1, v[0:1] sc0 sc1
	s_waitcnt vmcnt(0)
	v_mov_b32_e32 v14, v218
	s_lshl_b32 s4, s2, 3
	s_waitcnt lgkmcnt(0)
	s_barrier
	s_movk_i32 s3, 0x4100
	v_ashrrev_i32_e32 v0, 6, v14
	v_add_u32_e32 v0, s4, v0
	s_mov_b32 s12, 0
	v_cmp_gt_i32_e32 vcc, s3, v0
	v_mbcnt_lo_u32_b32 v214, -1, 0
	v_writelane_b32 v250, s4, 0
	v_readfirstlane_b32 s3, v1
	s_and_saveexec_b64 s[14:15], vcc
	s_cbranch_execz .LBB0_29
	s_load_dwordx4 s[8:11], s[0:1], 0x0
	v_and_b32_e32 v10, 63, v14
	v_ashrrev_i32_e32 v1, 31, v0
	v_lshlrev_b32_e32 v2, 2, v10
	s_lshl_b32 s16, s33, 3
	v_lshlrev_b64 v[8:9], 11, v[0:1]
	v_mbcnt_hi_u32_b32 v15, -1, v214
	v_cmp_eq_u32_e32 vcc, 0, v10
	v_mov_b64_e32 v[4:5], 0xe9a8000
	s_ashr_i32 s17, s16, 31
	v_lshlrev_b64 v[6:7], 12, v[0:1]
	v_lshl_or_b32 v8, v10, 4, v8
	v_lshlrev_b32_e32 v10, 3, v2
	v_and_b32_e32 v2, 64, v15
	v_mov_b32_e32 v3, 0
	v_lshl_add_u64 v[4:5], v[0:1], 2, v[4:5]
	s_lshl_b64 s[18:19], s[16:17], 2
	s_waitcnt lgkmcnt(0)
	v_lshl_add_u64 v[6:7], s[8:9], 0, v[6:7]
	s_lshl_b64 s[8:9], s[16:17], 12
	s_lshl_b64 s[20:21], s[16:17], 11
	s_mov_b64 s[22:23], 0
	s_movk_i32 s4, 0x407f
	s_movk_i32 s5, 0x4000
	v_mov_b32_e32 v1, 0x358637bd
	s_mov_b32 s17, 0x800000
	s_movk_i32 s30, 0x40ff
	v_xor_b32_e32 v16, 1, v15
	v_add_u32_e32 v17, 64, v2
	v_xor_b32_e32 v18, 2, v15
	v_xor_b32_e32 v19, 4, v15
	v_xor_b32_e32 v20, 8, v15
	v_xor_b32_e32 v21, 16, v15
	v_xor_b32_e32 v22, 32, v15
	s_branch .LBB0_21

.LBB0_24:
	s_mov_b32 s13, s12
	v_mov_b64_e32 v[24:25], s[12:13]
	v_mov_b64_e32 v[26:27], s[12:13]
	s_and_b64 s[24:25], vcc, exec
	global_store_dwordx4 v[12:13], v[24:27], off
	global_store_dwordx4 v[12:13], v[24:27], off offset:1024
	s_or_saveexec_b64 s[26:27], s[6:7]
	v_mov_b32_e32 v2, 0
	s_xor_b64 exec, exec, s[26:27]
	s_cbranch_execz .LBB0_23
.LBB0_25:
	v_add_u32_e32 v2, 0xffffc000, v0
	v_lshlrev_b64 v[24:25], 12, v[2:3]
	v_lshl_add_u64 v[24:25], s[10:11], 0, v[24:25]
	v_cmp_gt_i32_e64 s[6:7], s5, v0
	v_mov_b32_e32 v11, v3
	s_nop 0
	v_cndmask_b32_e64 v25, v25, v7, s[6:7]
	v_cndmask_b32_e64 v24, v24, v6, s[6:7]
	v_lshl_add_u64 v[36:37], v[24:25], 0, v[10:11]
	global_load_dwordx4 v[24:27], v[36:37], off
	global_load_dwordx4 v[28:31], v[36:37], off offset:16
	global_load_dwordx4 v[32:35], v[36:37], off offset:2048
	global_load_dwordx4 v[36:39], v[36:37], off offset:2064
	s_waitcnt vmcnt(2)
	v_cvt_pk_bf16_f32 v40, v24, v25
	v_cvt_pk_bf16_f32 v41, v26, v27
	v_cvt_pk_bf16_f32 v42, v28, v29
	v_cvt_pk_bf16_f32 v43, v30, v31
	global_store_dwordx4 v[12:13], v[40:43], off
	v_mul_f32_e32 v11, v25, v25
	v_fmac_f32_e32 v11, v24, v24
	v_fmac_f32_e32 v11, v26, v26
	v_fmac_f32_e32 v11, v27, v27
	s_waitcnt lgkmcnt(0)
	v_mul_f32_e32 v23, v29, v29
	v_fmac_f32_e32 v23, v28, v28
	v_fmac_f32_e32 v23, v30, v30
	v_fmac_f32_e32 v23, v31, v31
	v_add_f32_e32 v11, v11, v23
	s_waitcnt vmcnt(1)
	v_cvt_pk_bf16_f32 v44, v32, v33
	v_cvt_pk_bf16_f32 v45, v34, v35
	v_cvt_pk_bf16_f32 v46, v36, v37
	v_cvt_pk_bf16_f32 v47, v38, v39
	global_store_dwordx4 v[12:13], v[44:47], off offset:1024
	v_mul_f32_e32 v23, v33, v33
	v_fmac_f32_e32 v23, v32, v32
	v_fmac_f32_e32 v23, v34, v34
	v_fmac_f32_e32 v23, v35, v35
	v_add_f32_e32 v11, v11, v23
	v_mul_f32_e32 v23, v37, v37
	v_fmac_f32_e32 v23, v36, v36
	v_fmac_f32_e32 v23, v38, v38
	v_fmac_f32_e32 v23, v39, v39
	v_add_f32_e32 v11, v11, v23
	s_mov_b64 s[6:7], s[24:25]
	s_nop 1
	v_add_f32_dpp v11, v11, v11 quad_perm:[1,0,3,2] row_mask:0xf bank_mask:0xf bound_ctrl:1
	s_nop 1
	v_add_f32_dpp v11, v11, v11 quad_perm:[2,3,0,1] row_mask:0xf bank_mask:0xf bound_ctrl:1
	s_nop 1
	v_add_f32_dpp v11, v11, v11 row_half_mirror row_mask:0xf bank_mask:0xf bound_ctrl:1
	s_nop 1
	v_add_f32_dpp v11, v11, v11 row_mirror row_mask:0xf bank_mask:0xf bound_ctrl:1
	v_mov_b32_e32 v23, v11
	s_nop 1
	v_permlane16_swap_b32_e32 v11, v23
	s_nop 0
	v_add_f32_e32 v11, v11, v23
	v_mov_b32_e32 v23, v11
	s_nop 1
	v_permlane32_swap_b32_e32 v11, v23
	s_nop 0
	v_add_f32_e32 v11, v11, v23
	v_mov_b32_e32 v23, 0
	s_and_saveexec_b64 s[28:29], vcc
	s_cbranch_execz .LBB0_27
	s_waitcnt lgkmcnt(0)
	v_add_f32_e32 v2, v11, v23
	v_fmamk_f32 v2, v2, 0x3a800000, v1
	v_mul_f32_e32 v11, 0x4b800000, v2
	v_cmp_gt_f32_e64 s[6:7], s17, v2
	s_nop 1
	v_cndmask_b32_e64 v2, v2, v11, s[6:7]
	v_rsq_f32_e32 v2, v2
	s_nop 0
	v_mul_f32_e32 v11, 0x45800000, v2
	v_cndmask_b32_e64 v2, v2, v11, s[6:7]
	s_or_b64 s[6:7], s[24:25], exec
